# E16b: hg pass1 chunk loop loads issued one iteration ahead into spare VGPRs (depth-2 prefetch)
# baseline (speedup 1.0000x reference)
; #define HG_LOAD(c_) do { _Pragma("unroll") for (int i = 0; i < 8; ++i) { const int tt = (c_) * CH + 8 * th + i; \
;       if (tt < LSC) { const int rr = rowmap(d, p0 + tt); lf[i] = Fb[(size_t)rr * 1024]; lv[i] = bf2f(Vb[(size_t)rr * 512]); if (PASS == 3) lq[i] = bf2f(Qb[(size_t)rr * 512]); else lq[i] = 0.f; } \
;       else { lf[i] = 1.f; lv[i] = 0.f; lq[i] = 0.f; } } } while (0)
; template <int PASS>
; __device__ __forceinline__ void hg_mfma_pass(const float* __restrict__ Fg, const bf16_t* __restrict__ Qg, const bf16_t* __restrict__ Vg, float* __restrict__ Sbuf, float* __restrict__ DL,
;                                              bf16_t* __restrict__ OUT, char* lds) {
;     ...
;   for (int it = blockIdx.x * 2 + hb; it < NSC * 8; it += gridDim.x * 2) {
;     const int sc = it >> 3, hd = it & 7, h = hd >> 1, d = hd & 1;
;     const float* Fb = Fg + d * 512 + h * 128 + k; const bf16_t* Qb = Qg + h * 128 + k; const bf16_t* Vb = Vg + h * 128 + k;
;     f32x4 S[8][2];
;     float* Sg = Sbuf + ((size_t)(sc * 8 + hd) * 128) * 128 + w * 32 + r16;
; #pragma unroll
;     for (int kt = 0; kt < 8; ++kt)
; #pragma unroll
;       for (int vt = 0; vt < 2; ++vt)
; #pragma unroll
;         for (int j = 0; j < 4; ++j) S[kt][vt][j] = (PASS == 1) ? 0.f : Sg[(size_t)(16 * kt + 4 * fq + j) * 128 + vt * 16];
;     float dprod = 1.f;
;     const int p0 = sc * LSC;
;     float lf[8], lq[8], lv[8];
;     ...
;     HG_LOAD(0);
.LBB0_2113:
	v_ashrrev_i32_e32 v113, 3, v68
	v_lshlrev_b32_e32 v0, 6, v68
	v_mul_lo_u32 v114, v113, s94
	v_and_b32_e32 v20, 0x180, v0
	v_add_u32_e32 v115, v114, v97
	v_lshlrev_b32_e32 v0, 1, v20
	v_mov_b32_e32 v1, v144
	v_cmp_lt_i32_e32 vcc, s81, v115
	v_lshl_add_u64 v[78:79], v[70:71], 0, v[0:1]
	v_or_b32_e32 v4, 1, v115
	v_cndmask_b32_e32 v0, v209, v210, vcc
	v_cmp_gt_i32_e32 vcc, s81, v115
	v_sub_u32_e32 v0, v0, v115
	v_cndmask_b32_e64 v0, v0, v115, s[8:9]
	v_cndmask_b32_e32 v5, v210, v209, vcc
	v_sub_u32_e32 v5, v5, v4
	v_ashrrev_i32_e32 v1, 31, v0
	v_cndmask_b32_e64 v4, v5, v4, s[8:9]
	v_lshlrev_b64 v[2:3], 10, v[0:1]
	v_ashrrev_i32_e32 v5, 31, v4
	v_lshl_add_u64 v[2:3], v[78:79], 0, v[2:3]
	v_lshlrev_b64 v[6:7], 10, v[4:5]
	v_lshl_add_u64 v[6:7], v[78:79], 0, v[6:7]
	global_load_ushort v21, v[2:3], off
	global_load_ushort v22, v[6:7], off
	v_or_b32_e32 v2, 2, v115
	v_cmp_lt_i32_e32 vcc, s81, v2
	v_or_b32_e32 v8, 3, v115
	s_movk_i32 s12, 0xfb
	v_cndmask_b32_e32 v3, v209, v210, vcc
	v_cmp_lt_i32_e32 vcc, s81, v8
	v_sub_u32_e32 v3, v3, v2
	v_cndmask_b32_e64 v2, v3, v2, s[8:9]
	v_cndmask_b32_e32 v9, v209, v210, vcc
	v_sub_u32_e32 v9, v9, v8
	v_ashrrev_i32_e32 v3, 31, v2
	v_cndmask_b32_e64 v8, v9, v8, s[8:9]
	v_lshlrev_b64 v[6:7], 10, v[2:3]
	v_ashrrev_i32_e32 v9, 31, v8
	v_lshl_add_u64 v[6:7], v[78:79], 0, v[6:7]
	v_lshlrev_b64 v[10:11], 10, v[8:9]
	v_cmp_lt_i32_e32 vcc, s12, v115
	s_movk_i32 s12, 0xfa
	v_lshl_add_u64 v[10:11], v[78:79], 0, v[10:11]
	global_load_ushort v23, v[6:7], off
	global_load_ushort v24, v[10:11], off
	v_add_u32_e32 v6, 4, v115
	v_cndmask_b32_e32 v7, v209, v210, vcc
	v_cmp_lt_i32_e32 vcc, s12, v115
	v_sub_u32_e32 v7, v7, v6
	v_add_u32_e32 v12, 5, v115
	v_cndmask_b32_e32 v13, v209, v210, vcc
	v_cndmask_b32_e64 v6, v7, v6, s[8:9]
	v_sub_u32_e32 v13, v13, v12
	v_ashrrev_i32_e32 v7, 31, v6
	v_cndmask_b32_e64 v12, v13, v12, s[8:9]
	v_lshlrev_b64 v[10:11], 10, v[6:7]
	v_ashrrev_i32_e32 v13, 31, v12
	s_movk_i32 s12, 0xf9
	v_lshl_add_u64 v[10:11], v[78:79], 0, v[10:11]
	v_lshlrev_b64 v[14:15], 10, v[12:13]
	v_cmp_lt_i32_e32 vcc, s12, v115
	v_lshl_add_u64 v[14:15], v[78:79], 0, v[14:15]
	global_load_ushort v25, v[10:11], off
	global_load_ushort v26, v[14:15], off
	v_cndmask_b32_e32 v11, v209, v210, vcc
	v_cmp_lt_i32_e32 vcc, s95, v115
	v_add_u32_e32 v10, 6, v115
	v_add_u32_e32 v16, 7, v115
	v_cndmask_b32_e32 v17, v209, v210, vcc
	v_sub_u32_e32 v11, v11, v10
	v_sub_u32_e32 v17, v17, v16
	v_cndmask_b32_e64 v10, v11, v10, s[8:9]
	v_cndmask_b32_e64 v16, v17, v16, s[8:9]
	v_ashrrev_i32_e32 v11, 31, v10
	v_ashrrev_i32_e32 v17, 31, v16
	v_lshlrev_b64 v[14:15], 10, v[10:11]
	v_lshlrev_b64 v[18:19], 10, v[16:17]
	v_lshl_add_u64 v[14:15], v[78:79], 0, v[14:15]
	v_lshl_add_u64 v[18:19], v[78:79], 0, v[18:19]
	global_load_ushort v18, v[18:19], off
	s_nop 0
	global_load_ushort v19, v[14:15], off
	v_lshlrev_b32_e32 v14, 2, v20
	v_mov_b32_e32 v15, v144
	v_lshl_add_u64 v[80:81], v[76:77], 0, v[14:15]
	v_lshlrev_b64 v[0:1], 12, v[0:1]
	v_lshl_add_u64 v[0:1], v[80:81], 0, v[0:1]
	global_load_dword v82, v[0:1], off
	v_lshlrev_b64 v[0:1], 12, v[4:5]
	v_lshl_add_u64 v[0:1], v[80:81], 0, v[0:1]
	global_load_dword v83, v[0:1], off
	v_lshlrev_b64 v[0:1], 12, v[2:3]
	v_lshl_add_u64 v[0:1], v[80:81], 0, v[0:1]
	global_load_dword v84, v[0:1], off
	v_lshlrev_b64 v[0:1], 12, v[8:9]
	v_lshl_add_u64 v[0:1], v[80:81], 0, v[0:1]
	global_load_dword v85, v[0:1], off
	v_lshlrev_b64 v[0:1], 12, v[6:7]
	v_lshl_add_u64 v[0:1], v[80:81], 0, v[0:1]
	global_load_dword v86, v[0:1], off
	v_lshlrev_b64 v[0:1], 12, v[12:13]
	v_lshl_add_u64 v[0:1], v[80:81], 0, v[0:1]
	global_load_dword v87, v[0:1], off
	v_lshlrev_b64 v[0:1], 12, v[10:11]
	v_lshl_add_u64 v[0:1], v[80:81], 0, v[0:1]
	global_load_dword v88, v[0:1], off
	v_lshlrev_b64 v[0:1], 12, v[16:17]
	v_lshl_add_u64 v[0:1], v[80:81], 0, v[0:1]
	global_load_dword v89, v[0:1], off
	v_mov_b32_e32 v0, 0
	s_waitcnt vmcnt(14)
	v_lshlrev_b32_e32 v91, 16, v22
	v_lshlrev_b32_e32 v90, 16, v21
	v_sub_u32_e32 v116, v108, v114
	v_mov_b32_e32 v111, 1.0
	s_mov_b32 s24, 0
	v_mov_b32_e32 v1, v0
	v_mov_b32_e32 v2, v0
	v_mov_b32_e32 v3, v0
	v_mov_b32_e32 v4, v0
	v_mov_b32_e32 v5, v0
	v_mov_b32_e32 v6, v0
	v_mov_b32_e32 v7, v0
	v_mov_b32_e32 v12, v0
	v_mov_b32_e32 v13, v0
	v_mov_b32_e32 v14, v0
	v_mov_b32_e32 v15, v0
	s_waitcnt vmcnt(13)
	v_lshlrev_b32_e32 v92, 16, v23
	s_waitcnt vmcnt(12)
	v_lshlrev_b32_e32 v69, 16, v24
	v_mov_b32_e32 v8, v0
	v_mov_b32_e32 v9, v0
	v_mov_b32_e32 v10, v0
	v_mov_b32_e32 v11, v0
	v_mov_b32_e32 v20, v0
	v_mov_b32_e32 v21, v0
	v_mov_b32_e32 v22, v0
	v_mov_b32_e32 v23, v0
	v_mov_b32_e32 v16, v0
	v_mov_b32_e32 v17, v0
	v_mov_b32_e32 v24, v0
	v_mov_b32_e32 v27, v0
	v_mov_b32_e32 v28, v0
	v_mov_b32_e32 v29, v0
	v_mov_b32_e32 v30, v0
	v_mov_b32_e32 v31, v0
	s_waitcnt vmcnt(11)
	v_lshlrev_b32_e32 v96, 16, v25
	s_waitcnt vmcnt(10)
	v_lshlrev_b32_e32 v93, 16, v26
	v_mov_b32_e32 v25, v0
	v_mov_b32_e32 v26, v0
	v_mov_b32_e32 v32, v0
	v_mov_b32_e32 v33, v0
	v_mov_b32_e32 v34, v0
	v_mov_b32_e32 v35, v0
	v_mov_b32_e32 v36, v0
	v_mov_b32_e32 v37, v0
	v_mov_b32_e32 v38, v0
	v_mov_b32_e32 v39, v0
	v_mov_b32_e32 v48, v0
	v_mov_b32_e32 v49, v0
	v_mov_b32_e32 v50, v0
	v_mov_b32_e32 v51, v0
	s_waitcnt vmcnt(9)
	v_lshlrev_b32_e32 v95, 16, v18
	s_waitcnt vmcnt(8)
; #define HG_LOAD(c_) do { _Pragma("unroll") for (int i = 0; i < 8; ++i) { const int tt = (c_) * CH + 8 * th + i; \
;       if (tt < LSC) { const int rr = rowmap(d, p0 + tt); lf[i] = Fb[(size_t)rr * 1024]; lv[i] = bf2f(Vb[(size_t)rr * 512]); if (PASS == 3) lq[i] = bf2f(Qb[(size_t)rr * 512]); else lq[i] = 0.f; } \
;       else { lf[i] = 1.f; lv[i] = 0.f; lq[i] = 0.f; } } } while (0)
; template <int PASS>
; __device__ __forceinline__ void hg_mfma_pass(const float* __restrict__ Fg, const bf16_t* __restrict__ Qg, const bf16_t* __restrict__ Vg, float* __restrict__ Sbuf, float* __restrict__ DL,
;                                              bf16_t* __restrict__ OUT, char* lds) {
;     ...
;     HG_LOAD(0);
	v_lshlrev_b32_e32 v94, 16, v19
	v_mov_b32_e32 v18, v0
	v_mov_b32_e32 v19, v0
	v_mov_b32_e32 v40, v0
	v_mov_b32_e32 v41, v0
	v_mov_b32_e32 v42, v0
	v_mov_b32_e32 v43, v0
	v_mov_b32_e32 v52, v0
	v_mov_b32_e32 v53, v0
	v_mov_b32_e32 v54, v0
	v_mov_b32_e32 v55, v0
	v_mov_b32_e32 v44, v0
	v_mov_b32_e32 v45, v0
	v_mov_b32_e32 v46, v0
	v_mov_b32_e32 v47, v0
	v_mov_b32_e32 v56, v0
	v_mov_b32_e32 v57, v0
	v_mov_b32_e32 v58, v0
	v_mov_b32_e32 v59, v0
	v_mov_b32_e32 v60, v0
	v_mov_b32_e32 v61, v0
	v_mov_b32_e32 v62, v0
	v_mov_b32_e32 v63, v0
	v_add_u32_e32 v150, s24, v115
	v_add_u32_e32 v146, 16, v150
	v_cmp_lt_i32_e32 vcc, s81, v146
	v_add_u32_e32 v152, 17, v150
	s_nop 0
	v_cndmask_b32_e32 v147, v209, v210, vcc
	v_cmp_lt_i32_e32 vcc, s81, v152
	v_add3_u32 v147, v147, v116, 7
	v_cndmask_b32_e64 v146, v147, v146, s[8:9]
	v_cndmask_b32_e32 v153, v209, v210, vcc
	v_add3_u32 v153, v153, v116, 6
	v_ashrrev_i32_e32 v147, 31, v146
	v_cndmask_b32_e64 v154, v153, v152, s[8:9]
	v_lshlrev_b64 v[148:149], 10, v[146:147]
	v_ashrrev_i32_e32 v155, 31, v154
	v_lshl_add_u64 v[148:149], v[78:79], 0, v[148:149]
	v_lshlrev_b64 v[152:153], 10, v[154:155]
	v_lshl_add_u64 v[152:153], v[78:79], 0, v[152:153]
	global_load_ushort v162, v[148:149], off
	global_load_ushort v163, v[152:153], off
	v_add_u32_e32 v148, 19, v150
	v_cmp_lt_i32_e32 vcc, s81, v148
	v_lshlrev_b64 v[146:147], 12, v[146:147]
	v_lshl_add_u64 v[146:147], v[80:81], 0, v[146:147]
	v_cndmask_b32_e32 v149, v209, v210, vcc
	v_add3_u32 v149, v149, v116, 4
	v_cndmask_b32_e64 v148, v149, v148, s[8:9]
	v_ashrrev_i32_e32 v149, 31, v148
	v_lshlrev_b64 v[152:153], 10, v[148:149]
	v_lshl_add_u64 v[152:153], v[78:79], 0, v[152:153]
	global_load_ushort v168, v[152:153], off
	v_lshlrev_b64 v[148:149], 12, v[148:149]
	global_load_dword v152, v[146:147], off
	v_lshlrev_b64 v[146:147], 12, v[154:155]
	v_lshl_add_u64 v[146:147], v[80:81], 0, v[146:147]
	global_load_dword v153, v[146:147], off
	v_add_u32_e32 v146, 18, v150
	v_cmp_lt_i32_e32 vcc, s81, v146
	v_lshl_add_u64 v[148:149], v[80:81], 0, v[148:149]
	s_nop 0
	v_cndmask_b32_e32 v147, v209, v210, vcc
	v_add3_u32 v147, v147, v116, 5
	v_cndmask_b32_e64 v146, v147, v146, s[8:9]
	v_ashrrev_i32_e32 v147, 31, v146
	v_lshlrev_b64 v[154:155], 12, v[146:147]
	v_lshlrev_b64 v[146:147], 10, v[146:147]
	v_lshl_add_u64 v[154:155], v[80:81], 0, v[154:155]
	v_lshl_add_u64 v[146:147], v[78:79], 0, v[146:147]
	global_load_dword v154, v[154:155], off
	s_nop 0
	global_load_dword v155, v[148:149], off
	global_load_ushort v170, v[146:147], off
	v_add_u32_e32 v146, 20, v150
	v_cmp_lt_i32_e32 vcc, s81, v146
	s_nop 1
	v_cndmask_b32_e32 v147, v209, v210, vcc
	v_add3_u32 v147, v147, v116, 3
	v_cndmask_b32_e64 v146, v147, v146, s[8:9]
	v_ashrrev_i32_e32 v147, 31, v146
	v_lshlrev_b64 v[148:149], 12, v[146:147]
	v_lshl_add_u64 v[148:149], v[80:81], 0, v[148:149]
	global_load_dword v156, v[148:149], off
	v_add_u32_e32 v148, 21, v150
	v_cmp_lt_i32_e32 vcc, s81, v148
	v_lshlrev_b64 v[146:147], 10, v[146:147]
	v_lshl_add_u64 v[146:147], v[78:79], 0, v[146:147]
	v_cndmask_b32_e32 v149, v209, v210, vcc
	v_add3_u32 v149, v149, v116, 2
	v_cndmask_b32_e64 v148, v149, v148, s[8:9]
	v_ashrrev_i32_e32 v149, 31, v148
	v_lshlrev_b64 v[158:159], 12, v[148:149]
	v_lshl_add_u64 v[158:159], v[80:81], 0, v[158:159]
	v_lshlrev_b64 v[148:149], 10, v[148:149]
	global_load_dword v157, v[158:159], off
	v_lshl_add_u64 v[148:149], v[78:79], 0, v[148:149]
	global_load_ushort v166, v[146:147], off
	global_load_ushort v172, v[148:149], off
	v_add_u32_e32 v146, 22, v150
	v_cmp_lt_i32_e32 vcc, s81, v146
	s_nop 1
	v_cndmask_b32_e32 v147, v209, v210, vcc
	v_add3_u32 v147, v147, v116, 1
	v_cndmask_b32_e64 v146, v147, v146, s[8:9]
	v_ashrrev_i32_e32 v147, 31, v146
	v_lshlrev_b64 v[148:149], 12, v[146:147]
	v_lshl_add_u64 v[148:149], v[80:81], 0, v[148:149]
	global_load_dword v158, v[148:149], off
	v_add_u32_e32 v148, 23, v150
	v_cmp_lt_i32_e32 vcc, s81, v148
	v_lshlrev_b64 v[146:147], 10, v[146:147]
	v_lshl_add_u64 v[146:147], v[78:79], 0, v[146:147]
	v_cndmask_b32_e32 v149, v209, v210, vcc
	v_add_u32_e32 v149, v149, v116
	v_cndmask_b32_e64 v148, v149, v148, s[8:9]
	v_ashrrev_i32_e32 v149, 31, v148
	v_lshlrev_b64 v[160:161], 12, v[148:149]
	v_lshl_add_u64 v[160:161], v[80:81], 0, v[160:161]
	v_lshlrev_b64 v[148:149], 10, v[148:149]
	global_load_dword v159, v[160:161], off
	v_lshl_add_u64 v[148:149], v[78:79], 0, v[148:149]
	global_load_ushort v164, v[146:147], off
	global_load_ushort v165, v[148:149], off
	s_branch .LBB0_2115
; #define HG_LOAD(c_) do { _Pragma("unroll") for (int i = 0; i < 8; ++i) { const int tt = (c_) * CH + 8 * th + i; \
;       if (tt < LSC) { const int rr = rowmap(d, p0 + tt); lf[i] = Fb[(size_t)rr * 1024]; lv[i] = bf2f(Vb[(size_t)rr * 512]); if (PASS == 3) lq[i] = bf2f(Qb[(size_t)rr * 512]); else lq[i] = 0.f; } \
;       else { lf[i] = 1.f; lv[i] = 0.f; lq[i] = 0.f; } } } while (0)
; template <int PASS>
; __device__ __forceinline__ void hg_mfma_pass(const float* __restrict__ Fg, const bf16_t* __restrict__ Qg, const bf16_t* __restrict__ Vg, float* __restrict__ Sbuf, float* __restrict__ DL,
;                                              bf16_t* __restrict__ OUT, char* lds) {
;     ...
;       *(u32x4*)(sKT + k * 16 + 8 * th) = (u32x4){kh[0], kh[1], kh[2], kh[3]};
;       *(u32x4*)(sVT + k * 16 + 8 * th) = (u32x4){vv[0], vv[1], vv[2], vv[3]};
;       if (th == 0) { const float dk = __expf(blast); sD[k] = dk; dprod *= dk; }
;       if (c + 1 < NCH) HG_LOAD(c + 1);
.LBB0_2114:
	s_or_b64 exec, exec, s[12:13]
	s_waitcnt vmcnt(0)
	v_mov_b32_e32 v82, v152
	v_mov_b32_e32 v83, v153
	v_mov_b32_e32 v84, v154
	v_mov_b32_e32 v85, v155
	v_mov_b32_e32 v86, v156
	v_mov_b32_e32 v87, v157
	v_mov_b32_e32 v88, v158
	v_mov_b32_e32 v89, v159
	v_lshlrev_b32_e32 v90, 16, v162
	v_lshlrev_b32_e32 v91, 16, v163
	v_lshlrev_b32_e32 v69, 16, v168
	v_lshlrev_b32_e32 v92, 16, v170
	v_lshlrev_b32_e32 v96, 16, v166
	v_lshlrev_b32_e32 v93, 16, v172
	v_lshlrev_b32_e32 v94, 16, v164
	v_lshlrev_b32_e32 v95, 16, v165
	v_add_u32_e32 v150, s24, v115
	v_add_u32_e32 v146, 32, v150
	v_cmp_lt_i32_e32 vcc, s81, v146
	v_add_u32_e32 v152, 33, v150
	s_nop 0
	v_cndmask_b32_e32 v147, v209, v210, vcc
	v_cmp_lt_i32_e32 vcc, s81, v152
	v_add3_u32 v147, v147, v116, -9
	v_cndmask_b32_e64 v146, v147, v146, s[8:9]
	v_cndmask_b32_e32 v153, v209, v210, vcc
	v_add3_u32 v153, v153, v116, -10
	v_ashrrev_i32_e32 v147, 31, v146
	v_cndmask_b32_e64 v154, v153, v152, s[8:9]
	v_lshlrev_b64 v[148:149], 10, v[146:147]
	v_ashrrev_i32_e32 v155, 31, v154
	v_lshl_add_u64 v[148:149], v[78:79], 0, v[148:149]
	v_lshlrev_b64 v[152:153], 10, v[154:155]
	v_lshl_add_u64 v[152:153], v[78:79], 0, v[152:153]
	global_load_ushort v162, v[148:149], off
	global_load_ushort v163, v[152:153], off
	v_add_u32_e32 v148, 35, v150
	v_cmp_lt_i32_e32 vcc, s81, v148
	v_lshlrev_b64 v[146:147], 12, v[146:147]
	v_lshl_add_u64 v[146:147], v[80:81], 0, v[146:147]
	v_cndmask_b32_e32 v149, v209, v210, vcc
	v_add3_u32 v149, v149, v116, -12
	v_cndmask_b32_e64 v148, v149, v148, s[8:9]
	v_ashrrev_i32_e32 v149, 31, v148
	v_lshlrev_b64 v[152:153], 10, v[148:149]
	v_lshl_add_u64 v[152:153], v[78:79], 0, v[152:153]
	global_load_ushort v168, v[152:153], off
	v_lshlrev_b64 v[148:149], 12, v[148:149]
	global_load_dword v152, v[146:147], off
	v_lshlrev_b64 v[146:147], 12, v[154:155]
	v_lshl_add_u64 v[146:147], v[80:81], 0, v[146:147]
	global_load_dword v153, v[146:147], off
	v_add_u32_e32 v146, 34, v150
	v_cmp_lt_i32_e32 vcc, s81, v146
	v_lshl_add_u64 v[148:149], v[80:81], 0, v[148:149]
	s_nop 0
	v_cndmask_b32_e32 v147, v209, v210, vcc
	v_add3_u32 v147, v147, v116, -11
	v_cndmask_b32_e64 v146, v147, v146, s[8:9]
	v_ashrrev_i32_e32 v147, 31, v146
	v_lshlrev_b64 v[154:155], 12, v[146:147]
	v_lshlrev_b64 v[146:147], 10, v[146:147]
	v_lshl_add_u64 v[154:155], v[80:81], 0, v[154:155]
	v_lshl_add_u64 v[146:147], v[78:79], 0, v[146:147]
	global_load_dword v154, v[154:155], off
	s_nop 0
	global_load_dword v155, v[148:149], off
	global_load_ushort v170, v[146:147], off
	v_add_u32_e32 v146, 36, v150
	v_cmp_lt_i32_e32 vcc, s81, v146
	s_nop 1
	v_cndmask_b32_e32 v147, v209, v210, vcc
	v_add3_u32 v147, v147, v116, -13
	v_cndmask_b32_e64 v146, v147, v146, s[8:9]
	v_ashrrev_i32_e32 v147, 31, v146
	v_lshlrev_b64 v[148:149], 12, v[146:147]
	v_lshl_add_u64 v[148:149], v[80:81], 0, v[148:149]
	global_load_dword v156, v[148:149], off
	v_add_u32_e32 v148, 37, v150
	v_cmp_lt_i32_e32 vcc, s81, v148
	v_lshlrev_b64 v[146:147], 10, v[146:147]
	v_lshl_add_u64 v[146:147], v[78:79], 0, v[146:147]
	v_cndmask_b32_e32 v149, v209, v210, vcc
	v_add3_u32 v149, v149, v116, -14
	v_cndmask_b32_e64 v148, v149, v148, s[8:9]
	v_ashrrev_i32_e32 v149, 31, v148
	v_lshlrev_b64 v[158:159], 12, v[148:149]
	v_lshl_add_u64 v[158:159], v[80:81], 0, v[158:159]
	v_lshlrev_b64 v[148:149], 10, v[148:149]
	global_load_dword v157, v[158:159], off
	v_lshl_add_u64 v[148:149], v[78:79], 0, v[148:149]
	global_load_ushort v166, v[146:147], off
	global_load_ushort v172, v[148:149], off
	v_add_u32_e32 v146, 38, v150
	v_cmp_lt_i32_e32 vcc, s81, v146
	s_nop 1
	v_cndmask_b32_e32 v147, v209, v210, vcc
	v_add3_u32 v147, v147, v116, -15
	v_cndmask_b32_e64 v146, v147, v146, s[8:9]
	v_ashrrev_i32_e32 v147, 31, v146
	v_lshlrev_b64 v[148:149], 12, v[146:147]
	v_lshl_add_u64 v[148:149], v[80:81], 0, v[148:149]
	global_load_dword v158, v[148:149], off
	v_add_u32_e32 v148, 39, v150
	v_cmp_lt_i32_e32 vcc, s81, v148
	v_lshlrev_b64 v[146:147], 10, v[146:147]
	v_lshl_add_u64 v[146:147], v[78:79], 0, v[146:147]
	v_cndmask_b32_e32 v149, v209, v210, vcc
	v_add3_u32 v149, v149, v116, -16
	v_cndmask_b32_e64 v148, v149, v148, s[8:9]
	v_ashrrev_i32_e32 v149, 31, v148
	v_lshlrev_b64 v[160:161], 12, v[148:149]
	v_lshl_add_u64 v[160:161], v[80:81], 0, v[160:161]
	v_lshlrev_b64 v[148:149], 10, v[148:149]
	global_load_dword v159, v[160:161], off
	v_lshl_add_u64 v[148:149], v[78:79], 0, v[148:149]
	global_load_ushort v164, v[146:147], off
	global_load_ushort v165, v[148:149], off
	v_mov_b32_e32 v124, v144
	v_mov_b32_e32 v125, v144
	v_mov_b32_e32 v145, v144
	s_add_i32 s24, s24, 16
	s_cmpk_eq_i32 s24, 0xf0
	s_waitcnt lgkmcnt(0)
	s_barrier
; template <int PASS>
; __device__ __forceinline__ void hg_mfma_pass(const float* __restrict__ Fg, const bf16_t* __restrict__ Qg, const bf16_t* __restrict__ Vg, float* __restrict__ Sbuf, float* __restrict__ DL,
;                                              bf16_t* __restrict__ OUT, char* lds) {
;     ...
; #pragma unroll
;       for (int kt = 0; kt < 8; ++kt) {
;         const bf16x8 KTf = mk8(*(const u32x2*)(sKT + (16 * kt + r16) * 16 + 4 * fq), (u32x2){0u, 0u});
;         const f32x4 dk4 = *(const f32x4*)(sD + 16 * kt + 4 * fq);
; #pragma unroll
;         for (int vt = 0; vt < 2; ++vt) S[kt][vt] = __builtin_amdgcn_mfma_f32_16x16x32_bf16(KTf, VT[vt], S[kt][vt] * dk4, 0, 0, 0);
;       }
	ds_read2st64_b64 v[118:121], v110 offset0:21 offset1:22
	s_nop 0
	v_add_u32_e32 v112, v104, v103
	ds_read2st64_b64 v[64:67], v109 offset0:29 offset1:30
	ds_read_b128 v[126:129], v112 offset:1024
	ds_read_b128 v[130:133], v112 offset:1152
	s_waitcnt lgkmcnt(3)
	v_mov_b32_e32 v122, v118
	v_mov_b32_e32 v123, v119
	s_waitcnt lgkmcnt(2)
	v_mov_b32_e32 v142, v64
	v_mov_b32_e32 v143, v65
	v_mov_b32_e32 v64, v66
	v_mov_b32_e32 v65, v67
	v_mov_b32_e32 v66, v144
	v_mov_b32_e32 v67, v144
	s_waitcnt lgkmcnt(1)
	v_pk_mul_f32 v[60:61], v[60:61], v[126:127]
	v_pk_mul_f32 v[62:63], v[62:63], v[128:129]
	v_pk_mul_f32 v[56:57], v[56:57], v[126:127]
	v_pk_mul_f32 v[58:59], v[58:59], v[128:129]
	ds_read_b128 v[126:129], v112 offset:1088
	s_waitcnt lgkmcnt(1)
	v_pk_mul_f32 v[40:41], v[40:41], v[130:131]
	v_pk_mul_f32 v[42:43], v[42:43], v[132:133]
	v_pk_mul_f32 v[48:49], v[48:49], v[130:131]
	v_pk_mul_f32 v[50:51], v[50:51], v[132:133]
	ds_read_b128 v[130:133], v112 offset:1216
	v_mfma_f32_16x16x32_bf16 v[60:63], v[122:125], v[142:145], v[60:63]
	v_mov_b32_e32 v118, v120
	v_mov_b32_e32 v119, v121
	v_mov_b32_e32 v120, v144
	v_mov_b32_e32 v121, v144
	v_mfma_f32_16x16x32_bf16 v[56:59], v[122:125], v[64:67], v[56:59]
	ds_read2st64_b64 v[122:125], v110 offset0:23 offset1:24
	s_waitcnt lgkmcnt(2)
	v_pk_mul_f32 v[44:45], v[44:45], v[126:127]
	v_pk_mul_f32 v[46:47], v[46:47], v[128:129]
	v_pk_mul_f32 v[52:53], v[52:53], v[126:127]
	v_pk_mul_f32 v[54:55], v[54:55], v[128:129]
	s_waitcnt lgkmcnt(1)
	v_pk_mul_f32 v[36:37], v[36:37], v[130:131]
	v_pk_mul_f32 v[38:39], v[38:39], v[132:133]
	v_pk_mul_f32 v[32:33], v[32:33], v[130:131]
	v_pk_mul_f32 v[34:35], v[34:35], v[132:133]
	ds_read_b128 v[130:133], v112 offset:1280
	v_mfma_f32_16x16x32_bf16 v[44:47], v[118:121], v[142:145], v[44:47]
	s_waitcnt lgkmcnt(1)
	v_mov_b32_e32 v126, v122
	v_mov_b32_e32 v127, v123
	v_mov_b32_e32 v128, v144
	v_mov_b32_e32 v129, v144
	v_mfma_f32_16x16x32_bf16 v[52:55], v[118:121], v[64:67], v[52:55]
	v_mov_b32_e32 v118, v124
	v_mov_b32_e32 v119, v125
	ds_read2st64_b64 v[122:125], v110 offset0:25 offset1:26
	s_waitcnt lgkmcnt(1)
	v_pk_mul_f32 v[28:29], v[28:29], v[130:131]
	v_pk_mul_f32 v[30:31], v[30:31], v[132:133]
	v_pk_mul_f32 v[24:25], v[24:25], v[130:131]
	v_pk_mul_f32 v[26:27], v[26:27], v[132:133]
	ds_read_b128 v[130:133], v112 offset:1344
	v_mfma_f32_16x16x32_bf16 v[40:43], v[126:129], v[142:145], v[40:43]
	s_nop 0
	s_nop 0
	s_nop 0
	v_mfma_f32_16x16x32_bf16 v[48:51], v[126:129], v[64:67], v[48:51]
	s_waitcnt lgkmcnt(1)
	v_mov_b32_e32 v126, v122
	v_mov_b32_e32 v127, v123
	s_waitcnt lgkmcnt(0)
	v_pk_mul_f32 v[16:17], v[16:17], v[130:131]
	v_mfma_f32_16x16x32_bf16 v[36:39], v[118:121], v[142:145], v[36:39]
	v_mul_f32_e64 v18, v18, v132
	v_mul_f32_e64 v19, v19, v133
	v_pk_mul_f32 v[20:21], v[20:21], v[130:131]
	v_pk_mul_f32 v[22:23], v[22:23], v[132:133]
	v_mfma_f32_16x16x32_bf16 v[32:35], v[118:121], v[64:67], v[32:35]
	v_mov_b32_e32 v118, v124
	v_mov_b32_e32 v119, v125
	ds_read2st64_b64 v[122:125], v110 offset0:27 offset1:28
	v_mfma_f32_16x16x32_bf16 v[28:31], v[126:129], v[142:145], v[28:31]
	ds_read_b128 v[130:133], v112 offset:1408
	s_nop 0
	v_add_u32_e32 v116, -16, v116
	v_mfma_f32_16x16x32_bf16 v[24:27], v[126:129], v[64:67], v[24:27]
	s_waitcnt lgkmcnt(1)
	v_mov_b32_e32 v126, v122
	v_mov_b32_e32 v127, v123
	s_nop 0
	v_mfma_f32_16x16x32_bf16 v[16:19], v[118:121], v[142:145], v[16:19]
	s_nop 0
	v_mfma_f32_16x16x32_bf16 v[20:23], v[118:121], v[64:67], v[20:23]
	v_mov_b32_e32 v118, v124
	v_mov_b32_e32 v119, v125
	ds_read_b128 v[122:125], v112 offset:1472
	s_waitcnt lgkmcnt(1)
	v_pk_mul_f32 v[8:9], v[8:9], v[130:131]
	v_pk_mul_f32 v[10:11], v[10:11], v[132:133]
	v_pk_mul_f32 v[12:13], v[12:13], v[130:131]
	v_pk_mul_f32 v[14:15], v[14:15], v[132:133]
	s_waitcnt lgkmcnt(0)
	v_pk_mul_f32 v[4:5], v[4:5], v[122:123]
	v_pk_mul_f32 v[6:7], v[6:7], v[124:125]
	v_pk_mul_f32 v[0:1], v[0:1], v[122:123]
	v_pk_mul_f32 v[2:3], v[2:3], v[124:125]
	v_mfma_f32_16x16x32_bf16 v[8:11], v[126:129], v[142:145], v[8:11]
	v_mfma_f32_16x16x32_bf16 v[12:15], v[126:129], v[64:67], v[12:15]
	v_mfma_f32_16x16x32_bf16 v[4:7], v[118:121], v[142:145], v[4:7]
	v_mfma_f32_16x16x32_bf16 v[0:3], v[118:121], v[64:67], v[0:3]
	s_cbranch_scc1 .LBB0_2117
; #define LDS_BARRIER() do { asm volatile("s_waitcnt lgkmcnt(0)" ::: "memory"); __builtin_amdgcn_s_barrier(); asm volatile("" ::: "memory"); } while (0)
; __device__ __forceinline__ unsigned cvt2(float lo, float hi) { const f32x2 v = {lo, hi}; const bf16x2_t r = __builtin_convertvector(v, bf16x2_t); return __builtin_bit_cast(unsigned, r); }
; __device__ __forceinline__ bf16_t f2bf2(float f) { return (bf16_t)(cvt2(f, 0.f) & 0xffffu); }
; template <int PASS>
; __device__ __forceinline__ void hg_mfma_pass(const float* __restrict__ Fg, const bf16_t* __restrict__ Qg, const bf16_t* __restrict__ Vg, float* __restrict__ Sbuf, float* __restrict__ DL,
;                                              bf16_t* __restrict__ OUT, char* lds) {
;     ...
;     for (int c = 0; c < NCH; ++c) {
;       float f8[8], q8[8], v8[8], b8[8];
; #pragma unroll
;       for (int i = 0; i < 8; ++i) { f8[i] = lf[i]; q8[i] = lq[i]; v8[i] = lv[i]; }
;       float run = 0.f;
; #pragma unroll
;       for (int i = 0; i < 8; ++i) { run += fmaxf(__logf(f8[i]), -60.f); b8[i] = run; }
;       sSum[th * 128 + k] = run;
;       LDS_BARRIER();
;       const float s0 = sSum[k], s1 = sSum[128 + k], blast = s0 + s1, boff = th ? s0 : 0.f;
;       unsigned kh[4], vv[4];
; #pragma unroll
;       for (int i = 0; i < 8; i += 2) {
;         float qt[2], kt_[2], khh[2];
; #pragma unroll
;         for (int e = 0; e < 2; ++e) { const float b = b8[i + e] + boff, omf = 1.f - f8[i + e];
;           qt[e] = q8[i + e] * __expf(b); kt_[e] = omf * __expf(fminf(-b, 85.f)); khh[e] = omf * __expf(blast - b); }
;         if (PASS == 3) { *(bf16_t*)(sQ + (8 * th + i) * QROW + k * 2) = f2bf2(qt[0]); *(bf16_t*)(sQ + (8 * th + i + 1) * QROW + k * 2) = f2bf2(qt[1]);
;                          *(bf16_t*)(sK + (8 * th + i) * QROW + k * 2) = f2bf2(kt_[0]); *(bf16_t*)(sK + (8 * th + i + 1) * QROW + k * 2) = f2bf2(kt_[1]); }
;         kh[i >> 1] = cvt2(khh[0], khh[1]); vv[i >> 1] = cvt2(v8[i], v8[i + 1]);
;       }
;       *(u32x4*)(sKT + k * 16 + 8 * th) = (u32x4){kh[0], kh[1], kh[2], kh[3]};
;       *(u32x4*)(sVT + k * 16 + 8 * th) = (u32x4){vv[0], vv[1], vv[2], vv[3]};
;       if (th == 0) { const float dk = __expf(blast); sD[k] = dk; dprod *= dk; }
.LBB0_2115:
	s_waitcnt vmcnt(23)
	v_cmp_gt_f32_e32 vcc, s57, v82
	s_waitcnt vmcnt(22)
	v_pk_add_f32 v[120:121], v[82:83], 1.0 op_sel_hi:[1,0] neg_lo:[1,0] neg_hi:[1,0]
	v_cndmask_b32_e64 v64, 0, 32, vcc
	v_ldexp_f32 v64, v82, v64
	v_log_f32_e32 v64, v64
	v_cndmask_b32_e32 v65, 0, v212, vcc
	v_cvt_pk_bf16_f32 v82, v90, v91
	s_waitcnt vmcnt(20)
	v_pk_add_f32 v[90:91], v[84:85], 1.0 op_sel_hi:[1,0] neg_lo:[1,0] neg_hi:[1,0]
	v_mul_f32_e32 v66, 0x3f317217, v64
	v_fma_f32 v66, v64, s43, -v66
	v_fmac_f32_e32 v66, 0x3377d1cf, v64
	v_fmac_f32_e32 v66, 0x3f317217, v64
	v_cmp_lt_f32_e64 vcc, |v64|, s52
	s_nop 1
	v_cndmask_b32_e32 v64, v64, v66, vcc
	v_cmp_gt_f32_e32 vcc, s57, v83
	v_sub_f32_e32 v64, v64, v65
	v_max_f32_e32 v64, 0xc2700000, v64
	v_cndmask_b32_e64 v66, 0, 32, vcc
	v_ldexp_f32 v66, v83, v66
	v_log_f32_e32 v66, v66
	v_add_f32_e32 v64, 0, v64
	v_cvt_pk_bf16_f32 v83, v92, v69
	v_mul_f32_e32 v65, 0x3f317217, v66
	v_fma_f32 v65, v66, s43, -v65
	v_fmac_f32_e32 v65, 0x3377d1cf, v66
	v_fmac_f32_e32 v65, 0x3f317217, v66
	v_cmp_lt_f32_e64 s[12:13], |v66|, s52
	s_nop 1
	v_cndmask_b32_e64 v65, v66, v65, s[12:13]
	v_cndmask_b32_e32 v66, 0, v212, vcc
	v_cmp_gt_f32_e32 vcc, s57, v84
	v_sub_f32_e32 v65, v65, v66
	v_max_f32_e32 v65, 0xc2700000, v65
	v_cndmask_b32_e64 v67, 0, 32, vcc
	v_ldexp_f32 v67, v84, v67
	v_log_f32_e32 v67, v67
	v_add_f32_e32 v112, v65, v64
	v_cndmask_b32_e32 v66, 0, v212, vcc
	v_cmp_gt_f32_e32 vcc, s57, v85
	v_mul_f32_e32 v65, 0x3f317217, v67
	v_fma_f32 v65, v67, s43, -v65
	v_fmac_f32_e32 v65, 0x3377d1cf, v67
	v_fmac_f32_e32 v65, 0x3f317217, v67
	v_cmp_lt_f32_e64 s[12:13], |v67|, s52
	v_cvt_pk_bf16_f32 v84, v96, v93
	s_nop 0
	v_cndmask_b32_e64 v65, v67, v65, s[12:13]
	v_cndmask_b32_e64 v67, 0, 32, vcc
	v_ldexp_f32 v67, v85, v67
	v_log_f32_e32 v67, v67
	v_sub_f32_e32 v65, v65, v66
	v_max_f32_e32 v65, 0xc2700000, v65
	v_add_f32_e32 v117, v65, v112
	v_mul_f32_e32 v65, 0x3f317217, v67
	v_fma_f32 v65, v67, s43, -v65
	v_fmac_f32_e32 v65, 0x3377d1cf, v67
	v_fmac_f32_e32 v65, 0x3f317217, v67
	v_cmp_lt_f32_e64 s[12:13], |v67|, s52
	v_cndmask_b32_e32 v66, 0, v212, vcc
	s_waitcnt vmcnt(19)
	v_cmp_gt_f32_e32 vcc, s57, v86
	v_cndmask_b32_e64 v65, v67, v65, s[12:13]
	v_sub_f32_e32 v65, v65, v66
	v_cndmask_b32_e64 v67, 0, 32, vcc
	v_ldexp_f32 v67, v86, v67
	v_log_f32_e32 v67, v67
	v_max_f32_e32 v65, 0xc2700000, v65
	v_add_f32_e32 v118, v65, v117
	v_cndmask_b32_e32 v66, 0, v212, vcc
	v_mul_f32_e32 v65, 0x3f317217, v67
	v_fma_f32 v65, v67, s43, -v65
	v_fmac_f32_e32 v65, 0x3377d1cf, v67
	v_fmac_f32_e32 v65, 0x3f317217, v67
	v_cmp_lt_f32_e64 s[12:13], |v67|, s52
	s_waitcnt vmcnt(18)
	v_cmp_gt_f32_e32 vcc, s57, v87
	v_cndmask_b32_e64 v65, v67, v65, s[12:13]
	s_nop 0
	v_cndmask_b32_e64 v67, 0, 32, vcc
	v_ldexp_f32 v67, v87, v67
	v_log_f32_e32 v67, v67
	v_sub_f32_e32 v65, v65, v66
	v_max_f32_e32 v65, 0xc2700000, v65
	v_add_f32_e32 v122, v65, v118
	v_mul_f32_e32 v65, 0x3f317217, v67
	v_fma_f32 v65, v67, s43, -v65
	v_fmac_f32_e32 v65, 0x3377d1cf, v67
	v_fmac_f32_e32 v65, 0x3f317217, v67
	v_cmp_lt_f32_e64 s[12:13], |v67|, s52
	v_cndmask_b32_e32 v66, 0, v212, vcc
	s_waitcnt vmcnt(17)
	v_cmp_gt_f32_e32 vcc, s57, v88
	v_cndmask_b32_e64 v65, v67, v65, s[12:13]
	v_sub_f32_e32 v65, v65, v66
	v_cndmask_b32_e64 v67, 0, 32, vcc
	v_ldexp_f32 v67, v88, v67
	v_log_f32_e32 v67, v67
	v_max_f32_e32 v65, 0xc2700000, v65
	v_add_f32_e32 v124, v65, v122
	v_cndmask_b32_e32 v66, 0, v212, vcc
	v_mul_f32_e32 v65, 0x3f317217, v67
	v_fma_f32 v65, v67, s43, -v65
	v_fmac_f32_e32 v65, 0x3377d1cf, v67
	v_fmac_f32_e32 v65, 0x3f317217, v67
	v_cmp_lt_f32_e64 s[12:13], |v67|, s52
	s_waitcnt vmcnt(16)
	v_cmp_gt_f32_e32 vcc, s57, v89
	v_cndmask_b32_e64 v65, v67, v65, s[12:13]
	s_nop 0
	v_cndmask_b32_e64 v67, 0, 32, vcc
	v_ldexp_f32 v67, v89, v67
	v_log_f32_e32 v67, v67
	v_sub_f32_e32 v65, v65, v66
	v_max_f32_e32 v65, 0xc2700000, v65
	v_add_f32_e32 v125, v65, v124
	v_mul_f32_e32 v65, 0x3f317217, v67
	v_fma_f32 v65, v67, s43, -v65
	v_fmac_f32_e32 v65, 0x3377d1cf, v67
	v_fmac_f32_e32 v65, 0x3f317217, v67
	v_cmp_lt_f32_e64 s[12:13], |v67|, s52
	v_cndmask_b32_e32 v66, 0, v212, vcc
	s_nop 0
	v_cndmask_b32_e64 v65, v67, v65, s[12:13]
	v_sub_f32_e32 v65, v65, v66
	v_max_f32_e32 v65, 0xc2700000, v65
	v_add_f32_e32 v65, v65, v125
	ds_write_b32 v98, v65
	s_waitcnt lgkmcnt(0)
	s_barrier
	ds_read2st64_b32 v[66:67], v99 offset1:2
	s_waitcnt lgkmcnt(0)
	v_cndmask_b32_e64 v119, v66, 0, s[6:7]
	v_add_f32_e32 v126, v64, v119
	v_add_f32_e32 v85, v118, v119
	v_mov_b32_e32 v64, v66
	v_mov_b32_e32 v118, v67
	v_add_f32_e32 v112, v112, v119
	v_pk_add_f32 v[64:65], v[64:65], v[118:119]
	v_add_f32_e32 v117, v117, v119
	v_add_f32_e32 v69, v122, v119
	v_sub_f32_e32 v66, v64, v126
	v_sub_f32_e32 v67, v64, v112
	v_pk_add_f32 v[122:123], v[86:87], 1.0 op_sel_hi:[1,0] neg_lo:[1,0] neg_hi:[1,0]
	v_mul_f32_e32 v66, 0x3fb8aa3b, v66
	v_mul_f32_e32 v67, 0x3fb8aa3b, v67
	v_sub_f32_e32 v86, v64, v117
	v_sub_f32_e32 v85, v64, v85
	v_sub_f32_e32 v69, v64, v69
	v_add_f32_e32 v87, v124, v119
	v_exp_f32_e32 v66, v66
	v_exp_f32_e32 v67, v67
	v_mul_f32_e32 v86, 0x3fb8aa3b, v86
	v_mul_f32_e32 v85, 0x3fb8aa3b, v85
	v_mul_f32_e32 v69, 0x3fb8aa3b, v69
	v_add_f32_e32 v96, v125, v119
	v_exp_f32_e32 v92, v86
	v_exp_f32_e32 v93, v85
	v_pk_add_f32 v[118:119], v[88:89], 1.0 op_sel_hi:[1,0] neg_lo:[1,0] neg_hi:[1,0]
	v_exp_f32_e32 v88, v69
	v_sub_f32_e32 v69, v64, v87
	v_mul_f32_e32 v69, 0x3fb8aa3b, v69
	v_exp_f32_e32 v89, v69
	v_sub_f32_e32 v69, v64, v96
	v_sub_f32_e32 v65, v64, v65
	v_pk_mul_f32 v[66:67], v[120:121], v[66:67]
	v_mul_f32_e32 v69, 0x3fb8aa3b, v69
	v_mul_f32_e32 v65, 0x3fb8aa3b, v65
	v_cvt_pk_bf16_f32 v86, v66, v67
	v_pk_mul_f32 v[66:67], v[90:91], v[92:93]
	v_exp_f32_e32 v90, v69
	v_exp_f32_e32 v91, v65
	v_cvt_pk_bf16_f32 v87, v66, v67
	v_pk_mul_f32 v[66:67], v[122:123], v[88:89]
	v_cvt_pk_bf16_f32 v85, v94, v95
	v_cvt_pk_bf16_f32 v88, v66, v67
	v_pk_mul_f32 v[66:67], v[118:119], v[90:91]
	s_nop 0
	v_cvt_pk_bf16_f32 v89, v66, v67
	ds_write_b128 v101, v[86:89] offset:10752
	ds_write_b128 v101, v[82:85] offset:14848
	s_and_saveexec_b64 s[12:13], s[6:7]
	s_cbranch_execz .LBB0_2114
	v_mul_f32_e32 v64, 0x3fb8aa3b, v64
	v_exp_f32_e32 v64, v64
	v_add_u32_e32 v65, v100, v102
	v_mul_f32_e32 v111, v111, v64
	ds_write_b32 v65, v64 offset:1024
	s_branch .LBB0_2114
